# GEMM k-loop: the 8 LDS-DMA loads issued back-to-back before the LDS reads
# baseline (speedup 1.0000x reference)
.LBB0_226:
	s_and_b32 s0, s19, 0x2000
	s_xor_b32 s1, s0, 0x2000
	s_lshl_b32 s0, s0, 1
	v_add_u32_e32 v0, s0, v151
	v_add_u32_e32 v159, s0, v152
	v_add_u32_e32 v126, v0, v157
	v_add_u32_e32 v164, v159, v157
	s_lshl_b32 s1, s1, 1
	v_readfirstlane_b32 s0, v250
	s_nop 0
	s_add_u32 m0, s0, s1
	s_nop 0
	global_load_lds_dwordx4 v246, s[98:99]
	s_add_u32 m0, m0, 0x8000
	global_load_lds_dwordx4 v246, s[100:101]
	s_add_u32 m0, m0, 0xffff8400
	global_load_lds_dwordx4 v247, s[98:99]
	s_add_u32 m0, m0, 0x8000
	global_load_lds_dwordx4 v247, s[100:101]
	s_add_u32 m0, m0, 0xffff8400
	global_load_lds_dwordx4 v248, s[98:99]
	s_add_u32 m0, m0, 0x8000
	global_load_lds_dwordx4 v248, s[100:101]
	s_add_u32 m0, m0, 0xffff8400
	global_load_lds_dwordx4 v249, s[98:99]
	s_add_u32 m0, m0, 0x8000
	global_load_lds_dwordx4 v249, s[100:101]
	ds_read_b128 v[82:85], v126
	ds_read_b128 v[86:89], v126 offset:2048
	ds_read_b128 v[122:125], v126 offset:4096
	ds_read_b128 v[126:129], v126 offset:6144
	ds_read_b128 v[130:133], v164 offset:32768
	ds_read_b128 v[134:137], v164 offset:34816
	ds_read_b128 v[160:163], v164 offset:36864
	ds_read_b128 v[164:167], v164 offset:38912
	v_add_u32_e32 v0, v0, v158
	ds_read_b128 v[214:217], v0
	ds_read_b128 v[218:221], v0 offset:2048
	ds_read_b128 v[222:225], v0 offset:4096
	ds_read_b128 v[226:229], v0 offset:6144
	v_add_u32_e32 v0, v159, v158
	ds_read_b128 v[230:233], v0 offset:32768
	ds_read_b128 v[234:237], v0 offset:34816
	ds_read_b128 v[238:241], v0 offset:36864
	s_setprio 1
	s_waitcnt lgkmcnt(7)
	ds_read_b128 v[242:245], v0 offset:38912
	s_add_u32 s98, s98, 0x80
	s_addc_u32 s99, s99, 0
	s_add_u32 s100, s100, 0x80
	s_addc_u32 s101, s101, 0
	v_mfma_f32_16x16x32_bf16 v[2:5], v[130:133], v[82:85], v[2:5]
	v_mfma_f32_16x16x32_bf16 v[6:9], v[134:137], v[82:85], v[6:9]
	v_mfma_f32_16x16x32_bf16 v[10:13], v[160:163], v[82:85], v[10:13]
	v_mfma_f32_16x16x32_bf16 v[14:17], v[164:167], v[82:85], v[14:17]
	v_mfma_f32_16x16x32_bf16 v[18:21], v[130:133], v[86:89], v[18:21]
	v_mfma_f32_16x16x32_bf16 v[22:25], v[134:137], v[86:89], v[22:25]
	v_mfma_f32_16x16x32_bf16 v[26:29], v[160:163], v[86:89], v[26:29]
	v_mfma_f32_16x16x32_bf16 v[30:33], v[164:167], v[86:89], v[30:33]
	v_mfma_f32_16x16x32_bf16 v[34:37], v[130:133], v[122:125], v[34:37]
	v_mfma_f32_16x16x32_bf16 v[38:41], v[134:137], v[122:125], v[38:41]
	v_mfma_f32_16x16x32_bf16 v[42:45], v[160:163], v[122:125], v[42:45]
	v_mfma_f32_16x16x32_bf16 v[46:49], v[164:167], v[122:125], v[46:49]
	v_mfma_f32_16x16x32_bf16 v[50:53], v[130:133], v[126:129], v[50:53]
	v_mfma_f32_16x16x32_bf16 v[54:57], v[134:137], v[126:129], v[54:57]
	v_mfma_f32_16x16x32_bf16 v[58:61], v[160:163], v[126:129], v[58:61]
	v_mfma_f32_16x16x32_bf16 v[62:65], v[164:167], v[126:129], v[62:65]
	s_waitcnt lgkmcnt(0)
	v_mfma_f32_16x16x32_bf16 v[2:5], v[230:233], v[214:217], v[2:5]
	v_mfma_f32_16x16x32_bf16 v[6:9], v[234:237], v[214:217], v[6:9]
	v_mfma_f32_16x16x32_bf16 v[10:13], v[238:241], v[214:217], v[10:13]
	v_mfma_f32_16x16x32_bf16 v[14:17], v[242:245], v[214:217], v[14:17]
	v_mfma_f32_16x16x32_bf16 v[18:21], v[230:233], v[218:221], v[18:21]
	v_mfma_f32_16x16x32_bf16 v[22:25], v[234:237], v[218:221], v[22:25]
	v_mfma_f32_16x16x32_bf16 v[26:29], v[238:241], v[218:221], v[26:29]
	v_mfma_f32_16x16x32_bf16 v[30:33], v[242:245], v[218:221], v[30:33]
	v_mfma_f32_16x16x32_bf16 v[34:37], v[230:233], v[222:225], v[34:37]
	v_mfma_f32_16x16x32_bf16 v[38:41], v[234:237], v[222:225], v[38:41]
	v_mfma_f32_16x16x32_bf16 v[42:45], v[238:241], v[222:225], v[42:45]
	v_mfma_f32_16x16x32_bf16 v[46:49], v[242:245], v[222:225], v[46:49]
	v_mfma_f32_16x16x32_bf16 v[50:53], v[230:233], v[226:229], v[50:53]
	v_mfma_f32_16x16x32_bf16 v[54:57], v[234:237], v[226:229], v[54:57]
	v_mfma_f32_16x16x32_bf16 v[58:61], v[238:241], v[226:229], v[58:61]
	v_mfma_f32_16x16x32_bf16 v[62:65], v[242:245], v[226:229], v[62:65]
	s_setprio 0
	s_addk_i32 s19, 0x2000
	s_waitcnt vmcnt(0)
	s_add_u32 s44, s44, 0x80
	s_addc_u32 s45, s45, 0
	s_cmpk_eq_i32 s44, 0x780
	s_waitcnt vmcnt(0)
	s_barrier
	s_cbranch_scc0 .LBB0_226
	s_andn2_b64 vcc, exec, s[42:43]
	s_cbranch_vccnz .LBB0_229
	v_lshl_add_u64 v[66:67], v[90:91], 0, s[46:47]
	v_readfirstlane_b32 s0, v138
	v_lshl_add_u64 v[68:69], v[66:67], 0, v[114:115]
	v_lshl_add_u64 v[74:75], v[92:93], 0, s[52:53]
	s_mov_b32 m0, s0
	v_readfirstlane_b32 s0, v139
	v_lshl_add_u64 v[76:77], v[74:75], 0, v[120:121]
	v_lshl_add_u64 v[78:79], v[74:75], 0, v[118:119]
	v_lshl_add_u64 v[80:81], v[74:75], 0, v[116:117]
	v_lshl_add_u64 v[74:75], v[74:75], 0, v[114:115]
	global_load_lds_dwordx4 v[68:69], off
	s_mov_b32 m0, s0
	v_readfirstlane_b32 s0, v140
	v_lshl_add_u64 v[70:71], v[66:67], 0, v[116:117]
	global_load_lds_dwordx4 v[74:75], off
	s_mov_b32 m0, s0
	v_readfirstlane_b32 s0, v141
	global_load_lds_dwordx4 v[70:71], off
	s_mov_b32 m0, s0
	v_readfirstlane_b32 s0, v142
	v_lshl_add_u64 v[72:73], v[66:67], 0, v[118:119]
	global_load_lds_dwordx4 v[80:81], off
	s_mov_b32 m0, s0
	v_readfirstlane_b32 s0, v143
	global_load_lds_dwordx4 v[72:73], off
	s_mov_b32 m0, s0
	v_readfirstlane_b32 s0, v144
	v_lshl_add_u64 v[66:67], v[66:67], 0, v[120:121]
	global_load_lds_dwordx4 v[78:79], off
	s_mov_b32 m0, s0
	v_readfirstlane_b32 s0, v145
	global_load_lds_dwordx4 v[66:67], off
	s_mov_b32 m0, s0
	s_nop 0
	global_load_lds_dwordx4 v[76:77], off

.LBB0_892:
	s_and_b32 s0, s19, 0x2000
	s_xor_b32 s1, s0, 0x2000
	s_lshl_b32 s0, s0, 1
	v_add_u32_e32 v95, s0, v125
	v_add_u32_e32 v162, s0, v126
	v_add_u32_e32 v142, v95, v128
	v_add_u32_e32 v158, v162, v128
	s_lshl_b32 s1, s1, 1
	v_readfirstlane_b32 s0, v250
	s_nop 0
	s_add_u32 m0, s0, s1
	s_nop 0
	global_load_lds_dwordx4 v246, s[98:99]
	s_add_u32 m0, m0, 0x8000
	global_load_lds_dwordx4 v246, s[100:101]
	s_add_u32 m0, m0, 0xffff8400
	global_load_lds_dwordx4 v247, s[98:99]
	s_add_u32 m0, m0, 0x8000
	global_load_lds_dwordx4 v247, s[100:101]
	s_add_u32 m0, m0, 0xffff8400
	global_load_lds_dwordx4 v248, s[98:99]
	s_add_u32 m0, m0, 0x8000
	global_load_lds_dwordx4 v248, s[100:101]
	s_add_u32 m0, m0, 0xffff8400
	global_load_lds_dwordx4 v249, s[98:99]
	s_add_u32 m0, m0, 0x8000
	global_load_lds_dwordx4 v249, s[100:101]
	ds_read_b128 v[130:133], v142
	ds_read_b128 v[134:137], v142 offset:2048
	ds_read_b128 v[138:141], v142 offset:4096
	ds_read_b128 v[142:145], v142 offset:6144
	ds_read_b128 v[146:149], v158 offset:32768
	ds_read_b128 v[150:153], v158 offset:34816
	ds_read_b128 v[154:157], v158 offset:36864
	ds_read_b128 v[158:161], v158 offset:38912
	v_add_u32_e32 v95, v95, v129
	ds_read_b128 v[214:217], v95
	ds_read_b128 v[218:221], v95 offset:2048
	ds_read_b128 v[222:225], v95 offset:4096
	ds_read_b128 v[226:229], v95 offset:6144
	v_add_u32_e32 v95, v162, v129
	ds_read_b128 v[230:233], v95 offset:32768
	ds_read_b128 v[234:237], v95 offset:34816
	ds_read_b128 v[238:241], v95 offset:36864
	s_setprio 1
	s_waitcnt lgkmcnt(7)
	ds_read_b128 v[242:245], v95 offset:38912
	s_add_u32 s98, s98, 0x80
	s_addc_u32 s99, s99, 0
	s_add_u32 s100, s100, 0x80
	s_addc_u32 s101, s101, 0
	v_mfma_f32_16x16x32_bf16 v[2:5], v[146:149], v[130:133], v[2:5]
	v_mfma_f32_16x16x32_bf16 v[6:9], v[150:153], v[130:133], v[6:9]
	v_mfma_f32_16x16x32_bf16 v[10:13], v[154:157], v[130:133], v[10:13]
	v_mfma_f32_16x16x32_bf16 v[14:17], v[158:161], v[130:133], v[14:17]
	v_mfma_f32_16x16x32_bf16 v[18:21], v[146:149], v[134:137], v[18:21]
	v_mfma_f32_16x16x32_bf16 v[22:25], v[150:153], v[134:137], v[22:25]
	v_mfma_f32_16x16x32_bf16 v[26:29], v[154:157], v[134:137], v[26:29]
	v_mfma_f32_16x16x32_bf16 v[30:33], v[158:161], v[134:137], v[30:33]
	v_mfma_f32_16x16x32_bf16 v[34:37], v[146:149], v[138:141], v[34:37]
	v_mfma_f32_16x16x32_bf16 v[38:41], v[150:153], v[138:141], v[38:41]
	v_mfma_f32_16x16x32_bf16 v[42:45], v[154:157], v[138:141], v[42:45]
	v_mfma_f32_16x16x32_bf16 v[46:49], v[158:161], v[138:141], v[46:49]
	v_mfma_f32_16x16x32_bf16 v[50:53], v[146:149], v[142:145], v[50:53]
	v_mfma_f32_16x16x32_bf16 v[54:57], v[150:153], v[142:145], v[54:57]
	v_mfma_f32_16x16x32_bf16 v[58:61], v[154:157], v[142:145], v[58:61]
	v_mfma_f32_16x16x32_bf16 v[62:65], v[158:161], v[142:145], v[62:65]
	s_waitcnt lgkmcnt(0)
	v_mfma_f32_16x16x32_bf16 v[2:5], v[230:233], v[214:217], v[2:5]
	v_mfma_f32_16x16x32_bf16 v[6:9], v[234:237], v[214:217], v[6:9]
	v_mfma_f32_16x16x32_bf16 v[10:13], v[238:241], v[214:217], v[10:13]
	v_mfma_f32_16x16x32_bf16 v[14:17], v[242:245], v[214:217], v[14:17]
	v_mfma_f32_16x16x32_bf16 v[18:21], v[230:233], v[218:221], v[18:21]
	v_mfma_f32_16x16x32_bf16 v[22:25], v[234:237], v[218:221], v[22:25]
	v_mfma_f32_16x16x32_bf16 v[26:29], v[238:241], v[218:221], v[26:29]
	v_mfma_f32_16x16x32_bf16 v[30:33], v[242:245], v[218:221], v[30:33]
	v_mfma_f32_16x16x32_bf16 v[34:37], v[230:233], v[222:225], v[34:37]
	v_mfma_f32_16x16x32_bf16 v[38:41], v[234:237], v[222:225], v[38:41]
	v_mfma_f32_16x16x32_bf16 v[42:45], v[238:241], v[222:225], v[42:45]
	v_mfma_f32_16x16x32_bf16 v[46:49], v[242:245], v[222:225], v[46:49]
	v_mfma_f32_16x16x32_bf16 v[50:53], v[230:233], v[226:229], v[50:53]
	v_mfma_f32_16x16x32_bf16 v[54:57], v[234:237], v[226:229], v[54:57]
	v_mfma_f32_16x16x32_bf16 v[58:61], v[238:241], v[226:229], v[58:61]
	v_mfma_f32_16x16x32_bf16 v[62:65], v[242:245], v[226:229], v[62:65]
	s_setprio 0
	s_waitcnt vmcnt(0)
	s_add_u32 s46, s46, 0x80
	s_addc_u32 s47, s47, 0
	s_addk_i32 s19, 0x2000
	s_cmpk_eq_i32 s46, 0x780
	s_waitcnt vmcnt(0)
	s_barrier
	s_cbranch_scc0 .LBB0_892
	s_andn2_b64 vcc, exec, s[44:45]
	s_cbranch_vccnz .LBB0_888
	v_lshl_add_u64 v[96:97], s[56:57], 1, v[66:67]
	v_readfirstlane_b32 s0, v113
	v_lshl_add_u64 v[98:99], v[96:97], 0, v[86:87]
	v_lshl_add_u64 v[104:105], s[52:53], 1, v[68:69]
	s_mov_b32 m0, s0
	v_readfirstlane_b32 s0, v114
	v_lshl_add_u64 v[106:107], v[104:105], 0, v[92:93]
	v_lshl_add_u64 v[108:109], v[104:105], 0, v[90:91]
	v_lshl_add_u64 v[110:111], v[104:105], 0, v[88:89]
	v_lshl_add_u64 v[104:105], v[104:105], 0, v[86:87]
	global_load_lds_dwordx4 v[98:99], off
	s_mov_b32 m0, s0
	v_readfirstlane_b32 s0, v115
	v_lshl_add_u64 v[100:101], v[96:97], 0, v[88:89]
	global_load_lds_dwordx4 v[104:105], off
	s_mov_b32 m0, s0
	v_readfirstlane_b32 s0, v116
	global_load_lds_dwordx4 v[100:101], off
	s_mov_b32 m0, s0
	v_readfirstlane_b32 s0, v117
	v_lshl_add_u64 v[102:103], v[96:97], 0, v[90:91]
	global_load_lds_dwordx4 v[110:111], off
	s_mov_b32 m0, s0
	v_readfirstlane_b32 s0, v118
	global_load_lds_dwordx4 v[102:103], off
	s_mov_b32 m0, s0
	v_readfirstlane_b32 s0, v119
	v_lshl_add_u64 v[96:97], v[96:97], 0, v[92:93]
	global_load_lds_dwordx4 v[108:109], off
	s_mov_b32 m0, s0
	v_readfirstlane_b32 s0, v120
	global_load_lds_dwordx4 v[96:97], off
	s_mov_b32 m0, s0
	s_nop 0
	global_load_lds_dwordx4 v[106:107], off
	s_branch .LBB0_888

.LBB0_1000:
	s_and_b32 s0, s33, 0x2000
	s_xor_b32 s1, s0, 0x2000
	s_lshl_b32 s0, s0, 1
	v_add_u32_e32 v0, s0, v123
	v_add_u32_e32 v129, s0, v124
	v_add_u32_e32 v142, v0, v127
	v_add_u32_e32 v158, v129, v127
	s_lshl_b32 s1, s1, 1
	v_readfirstlane_b32 s0, v250
	s_nop 0
	s_add_u32 m0, s0, s1
	s_nop 0
	global_load_lds_dwordx4 v246, s[98:99]
	s_add_u32 m0, m0, 0x8000
	global_load_lds_dwordx4 v246, s[100:101]
	s_add_u32 m0, m0, 0xffff8400
	global_load_lds_dwordx4 v247, s[98:99]
	s_add_u32 m0, m0, 0x8000
	global_load_lds_dwordx4 v247, s[100:101]
	s_add_u32 m0, m0, 0xffff8400
	global_load_lds_dwordx4 v248, s[98:99]
	s_add_u32 m0, m0, 0x8000
	global_load_lds_dwordx4 v248, s[100:101]
	s_add_u32 m0, m0, 0xffff8400
	global_load_lds_dwordx4 v249, s[98:99]
	s_add_u32 m0, m0, 0x8000
	global_load_lds_dwordx4 v249, s[100:101]
	ds_read_b128 v[130:133], v142
	ds_read_b128 v[134:137], v142 offset:2048
	ds_read_b128 v[138:141], v142 offset:4096
	ds_read_b128 v[142:145], v142 offset:6144
	ds_read_b128 v[146:149], v158 offset:32768
	ds_read_b128 v[150:153], v158 offset:34816
	ds_read_b128 v[154:157], v158 offset:36864
	ds_read_b128 v[158:161], v158 offset:38912
	v_add_u32_e32 v0, v0, v128
	ds_read_b128 v[214:217], v0
	ds_read_b128 v[218:221], v0 offset:2048
	ds_read_b128 v[222:225], v0 offset:4096
	ds_read_b128 v[226:229], v0 offset:6144
	v_add_u32_e32 v0, v129, v128
	ds_read_b128 v[230:233], v0 offset:32768
	ds_read_b128 v[234:237], v0 offset:34816
	ds_read_b128 v[238:241], v0 offset:36864
	s_setprio 1
	s_waitcnt lgkmcnt(7)
	ds_read_b128 v[242:245], v0 offset:38912
	s_add_u32 s98, s98, 0x80
	s_addc_u32 s99, s99, 0
	s_add_u32 s100, s100, 0x80
	s_addc_u32 s101, s101, 0
	v_mfma_f32_16x16x32_bf16 v[62:65], v[146:149], v[130:133], v[62:65]
	v_mfma_f32_16x16x32_bf16 v[58:61], v[150:153], v[130:133], v[58:61]
	v_mfma_f32_16x16x32_bf16 v[54:57], v[154:157], v[130:133], v[54:57]
	v_mfma_f32_16x16x32_bf16 v[50:53], v[158:161], v[130:133], v[50:53]
	v_mfma_f32_16x16x32_bf16 v[46:49], v[146:149], v[134:137], v[46:49]
	v_mfma_f32_16x16x32_bf16 v[42:45], v[150:153], v[134:137], v[42:45]
	v_mfma_f32_16x16x32_bf16 v[38:41], v[154:157], v[134:137], v[38:41]
	v_mfma_f32_16x16x32_bf16 v[34:37], v[158:161], v[134:137], v[34:37]
	v_mfma_f32_16x16x32_bf16 v[30:33], v[146:149], v[138:141], v[30:33]
	v_mfma_f32_16x16x32_bf16 v[26:29], v[150:153], v[138:141], v[26:29]
	v_mfma_f32_16x16x32_bf16 v[22:25], v[154:157], v[138:141], v[22:25]
	v_mfma_f32_16x16x32_bf16 v[18:21], v[158:161], v[138:141], v[18:21]
	v_mfma_f32_16x16x32_bf16 v[14:17], v[146:149], v[142:145], v[14:17]
	v_mfma_f32_16x16x32_bf16 v[10:13], v[150:153], v[142:145], v[10:13]
	v_mfma_f32_16x16x32_bf16 v[6:9], v[154:157], v[142:145], v[6:9]
	v_mfma_f32_16x16x32_bf16 v[2:5], v[158:161], v[142:145], v[2:5]
	s_waitcnt lgkmcnt(0)
	v_mfma_f32_16x16x32_bf16 v[62:65], v[230:233], v[214:217], v[62:65]
	v_mfma_f32_16x16x32_bf16 v[58:61], v[234:237], v[214:217], v[58:61]
	v_mfma_f32_16x16x32_bf16 v[54:57], v[238:241], v[214:217], v[54:57]
	v_mfma_f32_16x16x32_bf16 v[50:53], v[242:245], v[214:217], v[50:53]
	v_mfma_f32_16x16x32_bf16 v[46:49], v[230:233], v[218:221], v[46:49]
	v_mfma_f32_16x16x32_bf16 v[42:45], v[234:237], v[218:221], v[42:45]
	v_mfma_f32_16x16x32_bf16 v[38:41], v[238:241], v[218:221], v[38:41]
	v_mfma_f32_16x16x32_bf16 v[34:37], v[242:245], v[218:221], v[34:37]
	v_mfma_f32_16x16x32_bf16 v[30:33], v[230:233], v[222:225], v[30:33]
	v_mfma_f32_16x16x32_bf16 v[26:29], v[234:237], v[222:225], v[26:29]
	v_mfma_f32_16x16x32_bf16 v[22:25], v[238:241], v[222:225], v[22:25]
	v_mfma_f32_16x16x32_bf16 v[18:21], v[242:245], v[222:225], v[18:21]
	v_mfma_f32_16x16x32_bf16 v[14:17], v[230:233], v[226:229], v[14:17]
	v_mfma_f32_16x16x32_bf16 v[10:13], v[234:237], v[226:229], v[10:13]
	v_mfma_f32_16x16x32_bf16 v[6:9], v[238:241], v[226:229], v[6:9]
	v_mfma_f32_16x16x32_bf16 v[2:5], v[242:245], v[226:229], v[2:5]
	s_setprio 0
	s_addk_i32 s33, 0x2000
	s_waitcnt vmcnt(0)
	s_add_u32 s46, s46, 0x80
	s_addc_u32 s47, s47, 0
	s_cmpk_eq_i32 s46, 0x780
	s_waitcnt vmcnt(0)
	s_barrier
	s_cbranch_scc0 .LBB0_1000
	s_andn2_b64 vcc, exec, s[44:45]
	s_cbranch_vccnz .LBB0_996
	v_lshl_add_u64 v[94:95], v[66:67], 0, s[52:53]
	v_readfirstlane_b32 s0, v111
	v_lshl_add_u64 v[96:97], v[94:95], 0, v[86:87]
	v_lshl_add_u64 v[102:103], v[68:69], 0, s[56:57]
	s_mov_b32 m0, s0
	v_readfirstlane_b32 s0, v112
	v_lshl_add_u64 v[104:105], v[102:103], 0, v[92:93]
	v_lshl_add_u64 v[106:107], v[102:103], 0, v[90:91]
	v_lshl_add_u64 v[108:109], v[102:103], 0, v[88:89]
	v_lshl_add_u64 v[102:103], v[102:103], 0, v[86:87]
	global_load_lds_dwordx4 v[96:97], off
	s_mov_b32 m0, s0
	v_readfirstlane_b32 s0, v113
	v_lshl_add_u64 v[98:99], v[94:95], 0, v[88:89]
	global_load_lds_dwordx4 v[102:103], off
	s_mov_b32 m0, s0
	v_readfirstlane_b32 s0, v114
	global_load_lds_dwordx4 v[98:99], off
	s_mov_b32 m0, s0
	v_readfirstlane_b32 s0, v115
	v_lshl_add_u64 v[100:101], v[94:95], 0, v[90:91]
	global_load_lds_dwordx4 v[108:109], off
	s_mov_b32 m0, s0
	v_readfirstlane_b32 s0, v116
	global_load_lds_dwordx4 v[100:101], off
	s_mov_b32 m0, s0
	v_readfirstlane_b32 s0, v117
	v_lshl_add_u64 v[94:95], v[94:95], 0, v[92:93]
	global_load_lds_dwordx4 v[106:107], off
	s_mov_b32 m0, s0
	v_readfirstlane_b32 s0, v118
	global_load_lds_dwordx4 v[94:95], off
	s_mov_b32 m0, s0
	s_nop 0
	global_load_lds_dwordx4 v[104:105], off
	s_branch .LBB0_996

.LBB0_1058:
	s_and_b32 s0, s22, 0x2000
	s_xor_b32 s1, s0, 0x2000
	s_lshl_b32 s0, s0, 1
	v_add_u32_e32 v99, s0, v125
	v_add_u32_e32 v162, s0, v126
	v_add_u32_e32 v142, v99, v128
	v_add_u32_e32 v158, v162, v128
	s_lshl_b32 s1, s1, 1
	v_readfirstlane_b32 s0, v250
	s_nop 0
	s_add_u32 m0, s0, s1
	s_nop 0
	global_load_lds_dwordx4 v246, s[98:99]
	s_add_u32 m0, m0, 0x8000
	global_load_lds_dwordx4 v246, s[100:101]
	s_add_u32 m0, m0, 0xffff8400
	global_load_lds_dwordx4 v247, s[98:99]
	s_add_u32 m0, m0, 0x8000
	global_load_lds_dwordx4 v247, s[100:101]
	s_add_u32 m0, m0, 0xffff8400
	global_load_lds_dwordx4 v248, s[98:99]
	s_add_u32 m0, m0, 0x8000
	global_load_lds_dwordx4 v248, s[100:101]
	s_add_u32 m0, m0, 0xffff8400
	global_load_lds_dwordx4 v249, s[98:99]
	s_add_u32 m0, m0, 0x8000
	global_load_lds_dwordx4 v249, s[100:101]
	ds_read_b128 v[130:133], v142
	ds_read_b128 v[134:137], v142 offset:2048
	ds_read_b128 v[138:141], v142 offset:4096
	ds_read_b128 v[142:145], v142 offset:6144
	ds_read_b128 v[146:149], v158 offset:32768
	ds_read_b128 v[150:153], v158 offset:34816
	ds_read_b128 v[154:157], v158 offset:36864
	ds_read_b128 v[158:161], v158 offset:38912
	v_add_u32_e32 v99, v99, v129
	ds_read_b128 v[214:217], v99
	ds_read_b128 v[218:221], v99 offset:2048
	ds_read_b128 v[222:225], v99 offset:4096
	ds_read_b128 v[226:229], v99 offset:6144
	v_add_u32_e32 v99, v162, v129
	ds_read_b128 v[230:233], v99 offset:32768
	ds_read_b128 v[234:237], v99 offset:34816
	ds_read_b128 v[238:241], v99 offset:36864
	s_setprio 1
	s_waitcnt lgkmcnt(7)
	ds_read_b128 v[242:245], v99 offset:38912
	s_add_u32 s98, s98, 0x80
	s_addc_u32 s99, s99, 0
	s_add_u32 s100, s100, 0x80
	s_addc_u32 s101, s101, 0
	v_mfma_f32_16x16x32_bf16 v[2:5], v[146:149], v[130:133], v[2:5]
	v_mfma_f32_16x16x32_bf16 v[6:9], v[150:153], v[130:133], v[6:9]
	v_mfma_f32_16x16x32_bf16 v[10:13], v[154:157], v[130:133], v[10:13]
	v_mfma_f32_16x16x32_bf16 v[14:17], v[158:161], v[130:133], v[14:17]
	v_mfma_f32_16x16x32_bf16 v[18:21], v[146:149], v[134:137], v[18:21]
	v_mfma_f32_16x16x32_bf16 v[22:25], v[150:153], v[134:137], v[22:25]
	v_mfma_f32_16x16x32_bf16 v[26:29], v[154:157], v[134:137], v[26:29]
	v_mfma_f32_16x16x32_bf16 v[30:33], v[158:161], v[134:137], v[30:33]
	v_mfma_f32_16x16x32_bf16 v[34:37], v[146:149], v[138:141], v[34:37]
	v_mfma_f32_16x16x32_bf16 v[38:41], v[150:153], v[138:141], v[38:41]
	v_mfma_f32_16x16x32_bf16 v[42:45], v[154:157], v[138:141], v[42:45]
	v_mfma_f32_16x16x32_bf16 v[46:49], v[158:161], v[138:141], v[46:49]
	v_mfma_f32_16x16x32_bf16 v[50:53], v[146:149], v[142:145], v[50:53]
	v_mfma_f32_16x16x32_bf16 v[54:57], v[150:153], v[142:145], v[54:57]
	v_mfma_f32_16x16x32_bf16 v[58:61], v[154:157], v[142:145], v[58:61]
	v_mfma_f32_16x16x32_bf16 v[62:65], v[158:161], v[142:145], v[62:65]
	s_waitcnt lgkmcnt(0)
	v_mfma_f32_16x16x32_bf16 v[2:5], v[230:233], v[214:217], v[2:5]
	v_mfma_f32_16x16x32_bf16 v[6:9], v[234:237], v[214:217], v[6:9]
	v_mfma_f32_16x16x32_bf16 v[10:13], v[238:241], v[214:217], v[10:13]
	v_mfma_f32_16x16x32_bf16 v[14:17], v[242:245], v[214:217], v[14:17]
	v_mfma_f32_16x16x32_bf16 v[18:21], v[230:233], v[218:221], v[18:21]
	v_mfma_f32_16x16x32_bf16 v[22:25], v[234:237], v[218:221], v[22:25]
	v_mfma_f32_16x16x32_bf16 v[26:29], v[238:241], v[218:221], v[26:29]
	v_mfma_f32_16x16x32_bf16 v[30:33], v[242:245], v[218:221], v[30:33]
	v_mfma_f32_16x16x32_bf16 v[34:37], v[230:233], v[222:225], v[34:37]
	v_mfma_f32_16x16x32_bf16 v[38:41], v[234:237], v[222:225], v[38:41]
	v_mfma_f32_16x16x32_bf16 v[42:45], v[238:241], v[222:225], v[42:45]
	v_mfma_f32_16x16x32_bf16 v[46:49], v[242:245], v[222:225], v[46:49]
	v_mfma_f32_16x16x32_bf16 v[50:53], v[230:233], v[226:229], v[50:53]
	v_mfma_f32_16x16x32_bf16 v[54:57], v[234:237], v[226:229], v[54:57]
	v_mfma_f32_16x16x32_bf16 v[58:61], v[238:241], v[226:229], v[58:61]
	v_mfma_f32_16x16x32_bf16 v[62:65], v[242:245], v[226:229], v[62:65]
	s_setprio 0
	s_waitcnt vmcnt(0)
	s_add_u32 s42, s42, 0x80
	s_addc_u32 s43, s43, 0
	s_addk_i32 s22, 0x2000
	s_cmpk_eq_i32 s42, 0x1580
	s_waitcnt vmcnt(0)
	s_barrier
	s_cbranch_scc0 .LBB0_1058
	s_andn2_b64 vcc, exec, s[40:41]
	s_cbranch_vccnz .LBB0_1054
	v_lshl_add_u64 v[66:67], s[44:45], 1, v[78:79]
	v_readfirstlane_b32 s0, v113
	v_lshl_add_u64 v[68:69], v[66:67], 0, v[70:71]
	v_lshl_add_u64 v[104:105], s[46:47], 1, v[80:81]
	s_mov_b32 m0, s0
	v_readfirstlane_b32 s0, v114
	v_lshl_add_u64 v[106:107], v[104:105], 0, v[76:77]
	v_lshl_add_u64 v[108:109], v[104:105], 0, v[74:75]
	v_lshl_add_u64 v[110:111], v[104:105], 0, v[72:73]
	v_lshl_add_u64 v[104:105], v[104:105], 0, v[70:71]
	global_load_lds_dwordx4 v[68:69], off
	s_mov_b32 m0, s0
	v_readfirstlane_b32 s0, v115
	v_lshl_add_u64 v[100:101], v[66:67], 0, v[72:73]
	global_load_lds_dwordx4 v[104:105], off
	s_mov_b32 m0, s0
	v_readfirstlane_b32 s0, v116
	global_load_lds_dwordx4 v[100:101], off
	s_mov_b32 m0, s0
	v_readfirstlane_b32 s0, v117
	v_lshl_add_u64 v[102:103], v[66:67], 0, v[74:75]
	global_load_lds_dwordx4 v[110:111], off
	s_mov_b32 m0, s0
	v_readfirstlane_b32 s0, v118
	global_load_lds_dwordx4 v[102:103], off
	s_mov_b32 m0, s0
	v_readfirstlane_b32 s0, v119
	v_lshl_add_u64 v[66:67], v[66:67], 0, v[76:77]
	global_load_lds_dwordx4 v[108:109], off
	s_mov_b32 m0, s0
	v_readfirstlane_b32 s0, v120
	global_load_lds_dwordx4 v[66:67], off
	s_mov_b32 m0, s0
	s_nop 0
	global_load_lds_dwordx4 v[106:107], off
	s_branch .LBB0_1054
